# v18 + attention phase: alternate workgroups of each XCD start with their stick-breaking tasks (compute-bound) while the others start with the dilated ones (memory-bound), same tasks per workgroup
# speedup vs baseline: 1.0102x; 1.0102x over previous
.LBB0_371:
	s_add_u32 s0, s62, 0x63200000
	s_addc_u32 s1, s63, 0
	s_add_u32 s72, s62, 0x59200000
	s_addc_u32 s73, s63, 0
	v_writelane_b32 v254, s0, 32
	s_cmp_lt_i32 s88, 4
	s_nop 0
	v_writelane_b32 v254, s1, 33
	s_cselect_b64 s[0:1], -1, 0
	s_cmp_gt_i32 s89, 3
	s_cselect_b64 s[2:3], -1, 0
	s_and_b64 s[0:1], s[0:1], s[2:3]
	s_andn2_b64 vcc, exec, s[0:1]
	s_cbranch_vccnz .LBB0_468
	v_writelane_b32 v254, s57, 34
	v_writelane_b32 v254, s56, 35
	v_writelane_b32 v254, s82, 36
	s_cmpk_gt_i32 s87, 0x9ff
	s_nop 0
	v_writelane_b32 v254, s83, 37
	v_writelane_b32 v254, s87, 38
	s_cbranch_scc1 .LBB0_414
	v_and_b32_e32 v1, 32, v0
	v_cmp_eq_u32_e64 s[2:3], 0, v1
	v_lshrrev_b32_e32 v1, 5, v182
	v_lshrrev_b32_e32 v3, 3, v0
	v_and_b32_e32 v3, 2, v3
	v_bfe_u32 v5, v182, 1, 1
	v_lshlrev_b32_e32 v7, 1, v1
	v_lshlrev_b32_e32 v8, 3, v0
	v_bfe_u32 v2, v0, 2, 2
	v_or_b32_e32 v6, v5, v3
	v_and_b32_e32 v8, 8, v8
	v_bitop3_b32 v3, v5, v7, v3 bitop3:0x36
	v_lshlrev_b32_e32 v5, 11, v1
	v_lshl_or_b32 v8, v2, 6, v8
	v_lshl_or_b32 v2, v2, 8, v5
	v_lshl_or_b32 v5, v3, 4, v2
	v_bitop3_b32 v3, v7, v6, 1 bitop3:0x36
	v_lshl_or_b32 v2, v3, 4, v2
	v_lshlrev_b32_e32 v3, 1, v0
	v_lshrrev_b32_e32 v4, 1, v182
	v_and_b32_e32 v3, 8, v3
	v_cmp_gt_u32_e64 s[6:7], 2, v182
	v_readlane_b32 s4, v254, 16
	v_add_u32_e32 v167, v2, v8
	v_lshlrev_b32_e32 v2, 2, v0
	v_and_or_b32 v3, v4, 4, v3
	v_writelane_b32 v254, s6, 39
	s_add_u32 s74, s62, 0x55200000
	v_and_b32_e32 v2, 12, v2
	v_lshrrev_b32_e32 v6, 2, v3
	v_writelane_b32 v254, s7, 40
	s_addc_u32 s75, s63, 0
	s_lshl_b32 s0, s4, 2
	v_and_or_b32 v7, v0, 19, v3
	v_bitop3_b32 v9, v6, v1, v2 bitop3:0x36
	v_lshrrev_b32_e32 v6, 4, v182
	v_readlane_b32 s5, v254, 0
	s_add_i32 s97, s0, 0
	v_lshlrev_b32_e32 v181, 8, v7
	v_and_b32_e32 v7, 15, v0
	v_or_b32_e32 v2, s0, v6
	v_lshlrev_b32_e32 v6, 2, v6
	s_bfe_u32 s0, s5, 0x20006
	v_bitop3_b32 v11, s0, v7, v6 bitop3:0x36
	s_lshl_b32 s0, s4, 10
	v_lshlrev_b32_e32 v4, 3, v1
	s_add_i32 s94, s0, 0
	s_movk_i32 s0, 0x80
	s_movk_i32 s1, 0xc0
	v_and_b32_e32 v165, 31, v0
	v_or_b32_e32 v180, v5, v8
	v_bitop3_b32 v191, v5, 64, v8 bitop3:0x36
	v_bitop3_b32 v193, v5, s0, v8 bitop3:0x36
	v_bitop3_b32 v195, v5, s1, v8 bitop3:0x36
	v_or_b32_e32 v5, 1, v4
	v_cmp_lt_u32_e64 s[12:13], v5, v165
	v_or_b32_e32 v5, 2, v4
	v_cmp_lt_u32_e64 s[14:15], v5, v165
	v_or_b32_e32 v5, 3, v4
	v_cmp_lt_u32_e64 s[16:17], v5, v165
	v_or_b32_e32 v5, 4, v4
	v_cmp_lt_u32_e64 s[18:19], v5, v165
	v_or_b32_e32 v5, 5, v4
	v_cmp_lt_u32_e64 s[20:21], v5, v165
	v_or_b32_e32 v5, 6, v4
	v_cmp_lt_u32_e64 s[22:23], v5, v165
	v_or_b32_e32 v5, 7, v4
	v_cmp_lt_u32_e64 s[24:25], v5, v165
	v_or_b32_e32 v5, 16, v4
	v_cmp_lt_u32_e64 s[26:27], v5, v165
	v_or_b32_e32 v5, 17, v4
	s_add_i32 s97, s97, 0x10000
	v_cmp_lt_u32_e64 s[28:29], v5, v165
	v_or_b32_e32 v5, 18, v4
	v_cmp_lt_u32_e64 s[30:31], v5, v165
	v_or_b32_e32 v5, 19, v4
	s_cmpk_gt_u32 s5, 0x1bf
	v_cmp_lt_u32_e64 s[34:35], v5, v165
	v_or_b32_e32 v5, 20, v4
	s_cselect_b64 s[0:1], -1, 0
	v_cmp_lt_u32_e64 s[36:37], v5, v165
	v_or_b32_e32 v5, 21, v4
	v_writelane_b32 v254, s0, 0
	s_cmp_eq_u32 s4, 7
	v_mov_b32_e32 v3, 0
	v_cmp_lt_u32_e64 s[38:39], v5, v165
	v_or_b32_e32 v5, 22, v4
	v_writelane_b32 v254, s1, 1
	s_cselect_b64 s[82:83], -1, 0
	s_add_i32 s0, s4, -6
	v_lshlrev_b32_e32 v10, 5, v182
	v_lshlrev_b64 v[6:7], 11, v[2:3]
	v_lshlrev_b32_e32 v183, 4, v9
	v_cmp_lt_u32_e64 s[40:41], v5, v165
	v_or_b32_e32 v5, 23, v4
	v_lshlrev_b64 v[8:9], 10, v[2:3]
	v_readlane_b32 s78, v254, 38
	v_writelane_b32 v254, s0, 41
	s_add_i32 s0, s94, 0xc000
	s_mov_b32 s77, 0
	s_waitcnt vmcnt(0)
	v_lshlrev_b32_e32 v164, 3, v11
	v_xor_b32_e32 v184, 32, v183
	v_xor_b32_e32 v185, 64, v183
	v_xor_b32_e32 v186, 0x60, v183
	v_xor_b32_e32 v187, 0x80, v183
	v_xor_b32_e32 v188, 0xa0, v183
	v_xor_b32_e32 v189, 0xc0, v183
	v_xor_b32_e32 v190, 0xe0, v183
	v_cmp_gt_u32_e64 s[6:7], 32, v182
	v_xor_b32_e32 v192, 0x440, v167
	v_xor_b32_e32 v194, 0x480, v167
	v_xor_b32_e32 v196, 0x4c0, v167
	v_cmp_eq_u32_e64 s[8:9], 0, v182
	v_cmp_lt_u32_e64 s[10:11], v4, v165
	v_cmp_lt_u32_e64 s[42:43], v5, v165
	v_add_u32_e32 v197, 0, v181
	v_lshlrev_b32_e32 v166, 2, v1
	s_xor_b32 s95, s78, 15
	s_add_i32 s88, s78, 0xfffffa00
	s_add_i32 s47, s4, -11
	s_add_i32 s92, s4, -7
	v_or_b32_e32 v198, 0xe0, v4
	v_add_u32_e32 v199, s97, v10
	v_lshlrev_b64 v[168:169], 1, v[6:7]
	s_add_i32 s56, s94, 0x2000
	s_add_i32 s57, s94, 0x4000
	s_add_i32 s89, s94, 0x6000
	s_add_i32 s93, s94, 0x8000
	s_add_i32 s68, s94, 0xa000
	v_writelane_b32 v254, s0, 42
	s_add_i32 s0, s94, 0xe000
	s_mov_b32 s5, 0xc3000000
	v_lshlrev_b64 v[170:171], 1, v[8:9]
	s_mov_b32 s80, 0xf149f2ca
	v_mov_b32_e32 v200, 0x80
	v_mov_b32_e32 v201, 0x100
	v_mov_b32_e32 v202, 0x200
	v_mov_b32_e32 v203, 0x400
	v_mov_b32_e32 v204, 0x800
	v_mov_b32_e32 v205, 0x1000
	v_mov_b32_e32 v206, 0x2000
	v_mov_b32_e32 v207, 0x4000
	v_mov_b32_e32 v208, 0x8000
	v_lshlrev_b32_e32 v172, 1, v4
	v_mov_b32_e32 v209, 0xf149f2ca
	v_writelane_b32 v254, s0, 43
	v_writelane_b32 v254, s78, 44
	s_xor_b32 s0, s78, 15
	s_add_i32 s0, s0, s78
	s_nop 0
	v_writelane_b32 v254, s0, 46
	s_and_b32 s0, s78, 8
	s_cmp_eq_u32 s0, 0
	s_cbranch_scc1 .Lp3norot
.Lp3adv:
	s_cmpk_lt_i32 s78, 0x600
	s_cbranch_scc0 .Lp3advd
	s_add_i32 s78, s78, s96
	s_branch .Lp3adv
.Lp3advd:
	s_cmpk_lt_i32 s78, 0xa00
	s_cbranch_scc1 .Lp3norot
	v_readlane_b32 s78, v254, 44
	s_nop 1
.Lp3norot:
	v_writelane_b32 v254, s78, 45
	s_nop 0
	v_readlane_b32 s0, v254, 46
	s_sub_i32 s95, s0, s78
	s_add_i32 s88, s78, 0xfffffa00
	s_branch .LBB0_376

.LBB0_375:
	s_add_i32 s78, s78, s96
	s_cmpk_lt_i32 s78, 0xa00
	s_cbranch_scc1 .Lp3nowrap
	v_readlane_b32 s78, v254, 44
.Lp3nowrap:
	v_readlane_b32 s0, v254, 46
	v_readlane_b32 s1, v254, 45
	s_sub_i32 s95, s0, s78
	s_add_i32 s88, s78, 0xfffffa00
	s_cmp_lg_u32 s78, s1
	s_cbranch_scc0 .LBB0_414
